# scan: parked-state LDS image swizzled (rows 4..11 of each step block swap adjacent 16B slots) so the staging waves' ds_read_b128 fragment reads are bank-conflict free
# speedup vs baseline: 1.0143x; 1.0090x over previous
.LBB0_1044:
	v_readlane_b32 s0, v255, 40
	v_readlane_b32 s1, v255, 41
	s_andn2_b64 vcc, exec, s[0:1]
	s_cbranch_vccnz .LBB0_1103
	s_and_b32 s6, s2, 3
	v_readlane_b32 s7, v255, 0
	s_mov_b64 s[0:1], -1
	s_cmpk_lt_u32 s7, 0x100
	v_lshlrev_b32_e32 v22, 3, v169
	s_cbranch_scc0 .LBB0_1049
	v_readlane_b32 s1, v255, 5
	s_lshl_b32 s0, s6, 4
	s_lshl_b32 s1, s1, 2
	s_or_b32 s0, s1, s0
	v_or_b32_e32 v6, s0, v166
	s_setprio 3
	v_or_b32_e32 v2, s1, v166
	s_movk_i32 s0, 0x90
	v_mul_lo_u32 v2, v2, s0
	v_readlane_b32 s7, v255, 5
	s_add_i32 s7, s7, 1
	s_and_b32 s7, s7, 2
	s_lshl_b32 s7, s7, 3
	v_xor_b32_e32 v118, s7, v22
	v_add3_u32 v7, 0, v2, v118
	v_mov_b32_e32 v2, 0
	s_mov_b32 s0, 0
	v_mov_b32_e32 v3, v2
	v_mov_b32_e32 v4, v2
	v_mov_b32_e32 v5, v2
	v_lshlrev_b32_e32 v9, 4, v169
	v_lshlrev_b32_e32 v10, 2, v6
	v_mov_b32_e32 v11, v7
	v_add_u32_e32 v8, 0xb000, v7
	v_add_u32_e32 v114, 0x5000, v9
	v_add_u32_e32 v115, 0x5000, v10
	v_add_u32_e32 v116, 0x9000, v7
	v_add_u32_e32 v117, 0x9000, v8
	s_barrier

.LBB0_1049:
	s_and_b64 vcc, exec, s[0:1]
	s_cbranch_vccz .LBB0_1102
	s_ashr_i32 s0, s2, 5
	s_bfe_u32 s7, s2, 0x30002
	v_lshlrev_b32_e32 v2, 2, v169
	s_ashr_i32 s1, s0, 31
	s_mul_i32 s10, s0, 0x1c8e400
	v_lshl_or_b32 v28, s7, 6, v2
	v_mov_b32_e32 v29, 0
	s_mul_hi_i32 s11, s0, 0x1c8e400
	s_add_u32 s10, s38, s10
	v_lshlrev_b64 v[6:7], 2, v[28:29]
	s_addc_u32 s11, s39, s11
	v_lshlrev_b32_e32 v28, 1, v28
	v_lshl_add_u64 v[30:31], s[10:11], 0, v[28:29]
	s_mul_i32 s11, s0, 0x804000
	s_mul_hi_i32 s10, s0, 0x804000
	s_add_u32 s4, s4, s11
	s_addc_u32 s5, s5, s10
	v_lshl_add_u64 v[32:33], s[4:5], 0, v[28:29]
	s_add_u32 s4, s16, s11
	s_addc_u32 s5, s17, s10
	v_lshl_add_u64 v[34:35], s[4:5], 0, v[28:29]
	s_mul_i32 s5, s0, 0x40200
	s_mul_hi_i32 s4, s0, 0x40200
	s_add_u32 s5, s28, s5
	s_addc_u32 s4, s29, s4
	s_lshl_b32 s10, s7, 2
	s_add_u32 s5, s5, s10
	s_addc_u32 s4, s4, 0
	s_add_u32 s36, s5, 0xfd30000
	s_addc_u32 s37, s4, 0
	s_lshl_b64 s[0:1], s[0:1], 23
	s_add_u32 s0, s44, s0
	s_addc_u32 s1, s45, s1
	s_lshl_b32 s4, s7, 7
	s_add_u32 s0, s0, s4
	s_addc_u32 s1, s1, 0
	s_lshl_b32 s4, s6, 5
	s_add_u32 s0, s0, s4
	s_addc_u32 s1, s1, 0
	s_add_u32 s40, s28, 0xfdf3f00
	v_readlane_b32 s4, v255, 5
	s_addc_u32 s41, s29, 0
	s_lshl_b32 s35, s4, 2
	v_lshlrev_b32_e32 v28, 3, v166
	s_add_i32 s62, s35, -16
	v_lshl_add_u64 v[26:27], s[0:1], 0, v[28:29]
	v_or_b32_e32 v28, s62, v166
	s_movk_i32 s63, 0xe40
	v_mad_u64_u32 v[2:3], s[0:1], v28, s63, v[30:31]
	v_max_i32_e32 v4, 1, v28
	global_load_dwordx2 v[24:25], v[2:3], off
	global_load_dwordx2 v[50:51], v[2:3], off offset:1024
	global_load_dwordx2 v[52:53], v[2:3], off offset:2048
	v_add_u32_e32 v2, -1, v4
	v_mad_u64_u32 v[2:3], s[0:1], v2, s63, v[30:31]
	v_readlane_b32 s64, v255, 7
	global_load_dwordx2 v[54:55], v[2:3], off
	global_load_dwordx2 v[56:57], v[2:3], off offset:1024
	global_load_dwordx2 v[58:59], v[2:3], off offset:2048
	v_lshlrev_b64 v[2:3], 10, v[28:29]
	v_readlane_b32 s78, v255, 21
	v_readlane_b32 s79, v255, 22
	v_lshl_add_u64 v[4:5], v[32:33], 0, v[2:3]
	v_lshl_add_u64 v[2:3], v[34:35], 0, v[2:3]
	v_lshl_add_u64 v[18:19], s[78:79], 0, v[6:7]
	global_load_dwordx2 v[60:61], v[4:5], off
	global_load_dwordx2 v[62:63], v[2:3], off
	v_lshl_add_u64 v[10:11], s[46:47], 0, v[6:7]
	global_load_dwordx4 v[2:5], v[18:19], off
	v_lshl_add_u64 v[14:15], s[48:49], 0, v[6:7]
	global_load_dwordx4 v[6:9], v[18:19], off offset:2048
	v_add_co_u32_e32 v18, vcc, 0x1000, v18
	global_load_dwordx4 v[10:13], v[10:11], off
	s_nop 0
	global_load_dwordx4 v[14:17], v[14:15], off
	v_addc_co_u32_e32 v19, vcc, 0, v19, vcc
	global_load_dwordx4 v[18:21], v[18:19], off
	v_or_b32_e32 v36, s35, v166
	v_add_u32_e32 v23, -1, v36
	v_cmp_eq_u32_e32 vcc, 0, v28
	v_mov_b32_e32 v37, v29
	v_mad_u64_u32 v[42:43], s[0:1], v36, s63, v[30:31]
	v_mad_u64_u32 v[46:47], s[0:1], v23, s63, v[30:31]
	v_cndmask_b32_e64 v72, 1.0, 0, vcc
	v_lshlrev_b64 v[38:39], 10, v[36:37]
	v_lshlrev_b64 v[40:41], 5, v[28:29]
	s_add_i32 s0, s35, 16
	v_lshlrev_b64 v[36:37], 5, v[36:37]
	v_lshl_add_u64 v[48:49], v[32:33], 0, v[38:39]
	v_lshl_add_u64 v[64:65], v[34:35], 0, v[38:39]
	v_lshl_add_u64 v[38:39], s[36:37], 0, v[40:41]
	v_lshl_add_u64 v[66:67], s[36:37], 0, v[36:37]
	global_load_dwordx2 v[36:37], v[46:47], off
	global_load_dwordx2 v[44:45], v[46:47], off offset:1024
	s_nop 0
	global_load_dwordx2 v[46:47], v[46:47], off offset:2048
	s_nop 0
	global_load_dwordx2 v[48:49], v[48:49], off
	s_nop 0
	global_load_dword v86, v[38:39], off
	s_nop 0
	global_load_dwordx2 v[38:39], v[42:43], off
	global_load_dwordx2 v[40:41], v[42:43], off offset:1024
	s_nop 0
	global_load_dwordx2 v[42:43], v[42:43], off offset:2048
	s_cmp_eq_u32 s4, 4
	v_readlane_b32 s69, v255, 12
	s_cselect_b64 s[46:47], -1, 0
	v_readlane_b32 s70, v255, 13
	s_movk_i32 s6, 0x90
	s_add_i32 s69, s35, -15
	v_readlane_b32 s71, v255, 14
	s_add_i32 s70, s35, -14
	s_add_i32 s71, s35, -13
	v_readlane_b32 s65, v255, 8
	v_readlane_b32 s66, v255, 9
	v_readlane_b32 s67, v255, 10
	v_readlane_b32 s68, v255, 11
	v_readlane_b32 s72, v255, 15
	s_mov_b32 s57, 0
	v_cmp_eq_u32_e64 s[4:5], 0, v178
	s_sub_i32 s67, s3, 64
	s_lshl_b32 s68, s62, 7
	s_lshl_b32 s66, s69, 7
	s_lshl_b32 s65, s70, 7
	s_lshl_b32 s64, s71, 7
	s_mov_b32 s72, 0
	v_readlane_b32 s73, v255, 16
	v_readlane_b32 s74, v255, 17
	v_readlane_b32 s75, v255, 18
	v_readlane_b32 s76, v255, 19
	v_readlane_b32 s77, v255, 20
	s_waitcnt vmcnt(20)
	v_lshlrev_b32_e32 v68, 16, v24
	v_and_b32_e32 v69, 0xffff0000, v24
	s_waitcnt vmcnt(19)
	v_lshlrev_b32_e32 v74, 16, v50
	v_and_b32_e32 v75, 0xffff0000, v50
	v_lshlrev_b32_e32 v76, 16, v51
	v_and_b32_e32 v77, 0xffff0000, v51
	s_waitcnt vmcnt(18)
	v_lshlrev_b32_e32 v78, 16, v52
	v_and_b32_e32 v79, 0xffff0000, v52
	v_lshlrev_b32_e32 v80, 16, v53
	v_and_b32_e32 v81, 0xffff0000, v53
	s_waitcnt vmcnt(17)
	v_lshlrev_b32_e32 v50, 16, v54
	v_and_b32_e32 v51, 0xffff0000, v54
	v_lshlrev_b32_e32 v52, 16, v55
	v_and_b32_e32 v53, 0xffff0000, v55
	s_waitcnt vmcnt(16)
	v_lshlrev_b32_e32 v82, 16, v56
	v_and_b32_e32 v83, 0xffff0000, v56
	v_lshlrev_b32_e32 v54, 16, v57
	v_and_b32_e32 v55, 0xffff0000, v57
	v_xor_b32_e32 v57, 0x80000000, v69
	v_xor_b32_e32 v56, 0x80000000, v68
	v_lshlrev_b32_e32 v24, 16, v25
	v_and_b32_e32 v25, 0xffff0000, v25
	v_pk_fma_f32 v[50:51], v[72:73], v[50:51], v[56:57] op_sel_hi:[0,1,1]
	v_xor_b32_e32 v57, 0x80000000, v25
	v_xor_b32_e32 v56, 0x80000000, v24
	s_waitcnt vmcnt(12)
	v_pk_fma_f32 v[94:95], v[2:3], v[50:51], v[68:69]
	v_xor_b32_e32 v51, 0x80000000, v77
	v_xor_b32_e32 v50, 0x80000000, v76
	v_or_b32_e32 v68, s0, v166
	v_pk_fma_f32 v[52:53], v[72:73], v[52:53], v[56:57] op_sel_hi:[0,1,1]
	v_pk_fma_f32 v[96:97], v[72:73], v[54:55], v[50:51] op_sel_hi:[0,1,1]
	v_add_u32_e32 v50, -1, v68
	v_mad_u64_u32 v[54:55], s[0:1], v68, s63, v[30:31]
	v_lshlrev_b32_e32 v84, 16, v58
	v_and_b32_e32 v85, 0xffff0000, v58
	v_lshlrev_b32_e32 v88, 16, v59
	v_and_b32_e32 v89, 0xffff0000, v59
	v_lshlrev_b32_e32 v23, 16, v60
	v_and_b32_e32 v87, 0xffff0000, v60
	v_lshlrev_b32_e32 v104, 16, v61
	v_and_b32_e32 v105, 0xffff0000, v61
	v_lshlrev_b32_e32 v90, 16, v62
	v_and_b32_e32 v91, 0xffff0000, v62
	v_pk_fma_f32 v[24:25], v[4:5], v[52:53], v[24:25]
	v_mad_u64_u32 v[70:71], s[0:1], v50, s63, v[30:31]
	global_load_dwordx2 v[58:59], v[64:65], off
	global_load_dword v62, v[66:67], off
	global_load_dwordx2 v[50:51], v[54:55], off
	global_load_dwordx2 v[52:53], v[54:55], off offset:1024
	s_nop 0
	global_load_dwordx2 v[54:55], v[54:55], off offset:2048
	s_nop 0
	global_load_dwordx2 v[56:57], v[70:71], off
	global_load_dwordx2 v[60:61], v[70:71], off offset:1024
	global_load_dwordx2 v[64:65], v[70:71], off offset:2048
	v_mov_b32_e32 v69, v29
	v_lshlrev_b64 v[66:67], 10, v[68:69]
	v_lshl_add_u64 v[70:71], v[32:33], 0, v[66:67]
	v_lshl_add_u64 v[100:101], v[34:35], 0, v[66:67]
	v_lshlrev_b64 v[66:67], 5, v[68:69]
	v_lshl_add_u64 v[102:103], s[36:37], 0, v[66:67]
	global_load_dwordx2 v[66:67], v[70:71], off
	global_load_dwordx2 v[68:69], v[100:101], off
	s_nop 0
	global_load_dword v70, v[102:103], off
	v_xor_b32_e32 v99, 0x80000000, v75
	v_xor_b32_e32 v98, 0x80000000, v74
	v_pk_fma_f32 v[82:83], v[72:73], v[82:83], v[98:99] op_sel_hi:[0,1,1]
	v_mul_f32_e32 v23, 0xbfb8aa3b, v23
	s_waitcnt vmcnt(22)
	v_pk_fma_f32 v[98:99], v[6:7], v[82:83], v[74:75]
	v_exp_f32_e32 v82, v23
	v_mul_f32_e32 v23, 0xbfb8aa3b, v87
	v_xor_b32_e32 v75, 0x80000000, v79
	v_xor_b32_e32 v74, 0x80000000, v78
	v_exp_f32_e32 v83, v23
	v_mul_f32_e32 v23, 0xbfb8aa3b, v104
	v_pk_fma_f32 v[96:97], v[8:9], v[96:97], v[76:77]
	v_pk_fma_f32 v[74:75], v[72:73], v[84:85], v[74:75] op_sel_hi:[0,1,1]
	v_xor_b32_e32 v77, 0x80000000, v81
	v_xor_b32_e32 v76, 0x80000000, v80
	v_exp_f32_e32 v84, v23
	v_mul_f32_e32 v23, 0xbfb8aa3b, v105
	v_lshlrev_b32_e32 v92, 16, v63
	v_and_b32_e32 v93, 0xffff0000, v63
	v_pk_fma_f32 v[72:73], v[72:73], v[88:89], v[76:77] op_sel_hi:[0,1,1]
	v_exp_f32_e32 v85, v23
	s_movk_i32 s0, 0x500
	s_waitcnt vmcnt(19)
	v_pk_fma_f32 v[76:77], v[20:21], v[72:73], v[80:81]
	v_pk_add_f32 v[72:73], v[92:93], -1.0 op_sel_hi:[1,0]
	v_mul_lo_u32 v23, v28, s0
	v_pk_fma_f32 v[72:73], v[16:17], v[72:73], 1.0 op_sel_hi:[1,1,0]
	v_add_u32_e32 v23, 0, v23
	v_pk_mul_f32 v[80:81], v[96:97], v[72:73]
	v_lshl_add_u32 v73, v169, 4, v23
	ds_write_b128 v73, v[82:85]
	v_pk_mul_f32 v[82:83], v[12:13], v[96:97] neg_lo:[0,1] neg_hi:[0,1]
	v_pk_fma_f32 v[74:75], v[18:19], v[74:75], v[78:79]
	s_waitcnt vmcnt(14)
	v_pk_mul_f32 v[84:85], v[86:87], v[82:83] op_sel_hi:[0,1]
	v_pk_mul_f32 v[82:83], v[10:11], v[98:99] neg_lo:[0,1] neg_hi:[0,1]
	v_pk_add_f32 v[78:79], v[90:91], -1.0 op_sel_hi:[1,0]
	v_pk_mul_f32 v[82:83], v[86:87], v[82:83] op_sel_hi:[0,1]
	v_pk_fma_f32 v[78:79], v[14:15], v[78:79], 1.0 op_sel_hi:[1,1,0]
	ds_write_b128 v73, v[82:85] offset:256
	v_pk_mul_f32 v[84:85], v[84:85], v[92:93] neg_lo:[1,0] neg_hi:[1,0]
	v_pk_mul_f32 v[82:83], v[82:83], v[90:91] neg_lo:[1,0] neg_hi:[1,0]
	s_movk_i32 s0, 0xfb80
	v_pk_mul_f32 v[78:79], v[98:99], v[78:79]
	ds_write_b128 v73, v[82:85] offset:512
	ds_write_b128 v73, v[78:81] offset:768
	ds_write_b128 v73, v[74:77] offset:1024
	v_cvt_pk_bf16_f32 v77, v24, v25
	v_mul_lo_u32 v24, v28, s0
	v_cvt_pk_bf16_f32 v76, v94, v95
	v_add3_u32 v75, v23, v24, v22
	v_and_b32_e32 v22, 48, v0
	s_add_i32 s0, 0, 0x14000
	ds_write_b64 v75, v[76:77] offset:40960
	v_add_u32_e32 v76, s0, v22
	v_add_u32_e32 v63, 0, v22
	v_lshl_or_b32 v22, s62, 4, v169
	v_mul_lo_u32 v79, v22, s6
	v_lshl_or_b32 v22, s69, 4, v169
	v_mul_lo_u32 v74, v22, s6
	v_lshl_or_b32 v22, s70, 4, v169
	v_mul_lo_u32 v72, v22, s6
	v_lshl_or_b32 v22, s71, 4, v169
	v_cmp_eq_u32_e64 s[0:1], 0, v169
	v_add_u32_e32 v77, 48, v28
	v_or_b32_e32 v78, 64, v166
	v_mul_lo_u32 v71, v22, s6
	v_sub_u32_e32 v80, 0, v28
	v_add_u32_e32 v112, 4, v169
	v_and_b32_e32 v112, 8, v112
	v_lshlrev_b32_e32 v112, 1, v112
	v_xor_b32_e32 v113, v112, v76
	v_xor_b32_e32 v112, v112, v63
	s_waitcnt lgkmcnt(0)
	s_barrier
	s_branch .LBB0_1053

.LBB0_1066:
	s_or_b64 exec, exec, s[6:7]
	s_cmp_eq_u32 s72, 0
	s_cbranch_scc1 .LBB0_1076
	v_add_u32_e32 v28, v113, v79
	ds_read_b128 v[22:25], v28
	v_add_u32_e32 v81, s68, v63
	ds_read_b128 v[82:85], v28 offset:64
	ds_read_b128 v[86:89], v81 offset:43008
	ds_read_b128 v[90:93], v81 offset:43072
	s_lshl_b32 s10, s72, 4
	s_add_i32 s10, s10, -16
	s_add_i32 s11, s10, s62
	s_cmp_gt_i32 s11, 15
	s_cselect_b64 s[6:7], -1, 0
	s_and_b64 s[30:31], s[0:1], s[6:7]
	s_waitcnt lgkmcnt(1)
	v_mfma_f32_16x16x32_bf16 v[22:25], v[22:25], v[86:89], 0
	s_waitcnt lgkmcnt(0)
	v_mfma_f32_16x16x32_bf16 v[22:25], v[82:85], v[90:93], v[22:25]
	s_and_saveexec_b64 s[6:7], s[30:31]
	s_cbranch_execz .LBB0_1069
	s_add_i32 s56, s11, -16
	s_lshl_b64 s[30:31], s[56:57], 10
	s_nop 3
	v_cvt_pk_bf16_f32 v22, v22, v23
	v_cvt_pk_bf16_f32 v23, v24, v25
	v_lshl_add_u64 v[24:25], v[26:27], 0, s[30:31]
	global_store_dwordx2 v[24:25], v[22:23], off
.LBB0_1069:
	s_or_b64 exec, exec, s[6:7]
	v_add_u32_e32 v28, v113, v74
	s_nop 3
	ds_read_b128 v[22:25], v28
	v_add_u32_e32 v81, s66, v63
	ds_read_b128 v[82:85], v28 offset:64
	ds_read_b128 v[86:89], v81 offset:43008
	ds_read_b128 v[90:93], v81 offset:43072
	s_add_i32 s11, s10, s69
	s_cmp_gt_i32 s11, 15
	s_cselect_b64 s[6:7], -1, 0
	s_and_b64 s[30:31], s[0:1], s[6:7]
	s_waitcnt lgkmcnt(1)
	v_mfma_f32_16x16x32_bf16 v[22:25], v[22:25], v[86:89], 0
	s_waitcnt lgkmcnt(0)
	v_mfma_f32_16x16x32_bf16 v[22:25], v[82:85], v[90:93], v[22:25]
	s_and_saveexec_b64 s[6:7], s[30:31]
	s_cbranch_execz .LBB0_1071
	s_add_i32 s56, s11, -16
	s_lshl_b64 s[30:31], s[56:57], 10
	s_nop 3
	v_cvt_pk_bf16_f32 v22, v22, v23
	v_cvt_pk_bf16_f32 v23, v24, v25
	v_lshl_add_u64 v[24:25], v[26:27], 0, s[30:31]
	global_store_dwordx2 v[24:25], v[22:23], off
.LBB0_1071:
	s_or_b64 exec, exec, s[6:7]
	v_add_u32_e32 v28, v113, v72
	s_nop 3
	ds_read_b128 v[22:25], v28
	v_add_u32_e32 v81, s65, v63
	ds_read_b128 v[82:85], v28 offset:64
	ds_read_b128 v[86:89], v81 offset:43008
	ds_read_b128 v[90:93], v81 offset:43072
	s_add_i32 s11, s10, s70
	s_cmp_gt_i32 s11, 15
	s_cselect_b64 s[6:7], -1, 0
	s_and_b64 s[30:31], s[0:1], s[6:7]
	s_waitcnt lgkmcnt(1)
	v_mfma_f32_16x16x32_bf16 v[22:25], v[22:25], v[86:89], 0
	s_waitcnt lgkmcnt(0)
	v_mfma_f32_16x16x32_bf16 v[22:25], v[82:85], v[90:93], v[22:25]
	s_and_saveexec_b64 s[6:7], s[30:31]
	s_cbranch_execz .LBB0_1073
	s_add_i32 s56, s11, -16
	s_lshl_b64 s[30:31], s[56:57], 10
	s_nop 3
	v_cvt_pk_bf16_f32 v22, v22, v23
	v_cvt_pk_bf16_f32 v23, v24, v25
	v_lshl_add_u64 v[24:25], v[26:27], 0, s[30:31]
	global_store_dwordx2 v[24:25], v[22:23], off
.LBB0_1073:
	s_or_b64 exec, exec, s[6:7]
	v_add_u32_e32 v28, v113, v71
	s_nop 3
	ds_read_b128 v[22:25], v28
	v_add_u32_e32 v81, s64, v63
	ds_read_b128 v[82:85], v28 offset:64
	ds_read_b128 v[86:89], v81 offset:43008
	ds_read_b128 v[90:93], v81 offset:43072
	s_add_i32 s10, s10, s71
	s_cmp_gt_i32 s10, 15
	s_cselect_b64 s[6:7], -1, 0
	s_and_b64 s[30:31], s[0:1], s[6:7]
	s_waitcnt lgkmcnt(1)
	v_mfma_f32_16x16x32_bf16 v[22:25], v[22:25], v[86:89], 0
	s_waitcnt lgkmcnt(0)
	v_mfma_f32_16x16x32_bf16 v[22:25], v[82:85], v[90:93], v[22:25]
	s_and_saveexec_b64 s[6:7], s[30:31]
	s_cbranch_execz .LBB0_1075
	s_add_i32 s56, s10, -16
	s_lshl_b64 s[10:11], s[56:57], 10
	s_nop 3
	v_cvt_pk_bf16_f32 v22, v22, v23
	v_cvt_pk_bf16_f32 v23, v24, v25
	v_lshl_add_u64 v[24:25], v[26:27], 0, s[10:11]
	global_store_dwordx2 v[24:25], v[22:23], off

.LBB0_1079:
	s_andn2_b64 vcc, exec, s[30:31]
	s_waitcnt lgkmcnt(0)
	s_barrier
	s_cbranch_vccnz .LBB0_1052
	v_add_u32_e32 v28, v112, v79
	ds_read_b128 v[22:25], v28 offset:45056
	v_add_u32_e32 v81, s68, v63
	ds_read_b128 v[82:85], v28 offset:45120
	ds_read_b128 v[86:89], v81 offset:40960
	ds_read_b128 v[90:93], v81 offset:41024
	s_lshl_b32 s11, s72, 4
	s_add_i32 s10, s62, s11
	s_cmp_gt_i32 s10, 15
	s_cselect_b64 s[6:7], -1, 0
	s_and_b64 s[30:31], s[0:1], s[6:7]
	s_waitcnt lgkmcnt(1)
	v_mfma_f32_16x16x32_bf16 v[22:25], v[22:25], v[86:89], 0
	s_waitcnt lgkmcnt(0)
	v_mfma_f32_16x16x32_bf16 v[22:25], v[82:85], v[90:93], v[22:25]
	s_and_saveexec_b64 s[6:7], s[30:31]
	s_cbranch_execz .LBB0_1082
	s_add_i32 s56, s10, -16
	s_lshl_b64 s[30:31], s[56:57], 10
	s_nop 3
	v_cvt_pk_bf16_f32 v22, v22, v23
	v_cvt_pk_bf16_f32 v23, v24, v25
	v_lshl_add_u64 v[24:25], v[26:27], 0, s[30:31]
	global_store_dwordx2 v[24:25], v[22:23], off
.LBB0_1082:
	s_or_b64 exec, exec, s[6:7]
	v_add_u32_e32 v28, v112, v74
	s_nop 3
	ds_read_b128 v[22:25], v28 offset:45056
	v_add_u32_e32 v81, s66, v63
	ds_read_b128 v[82:85], v28 offset:45120
	ds_read_b128 v[86:89], v81 offset:40960
	ds_read_b128 v[90:93], v81 offset:41024
	s_add_i32 s30, s69, s11
	s_cmp_gt_i32 s30, 15
	s_cselect_b64 s[6:7], -1, 0
	s_and_b64 s[74:75], s[0:1], s[6:7]
	s_waitcnt lgkmcnt(1)
	v_mfma_f32_16x16x32_bf16 v[22:25], v[22:25], v[86:89], 0
	s_waitcnt lgkmcnt(0)
	v_mfma_f32_16x16x32_bf16 v[22:25], v[82:85], v[90:93], v[22:25]
	s_and_saveexec_b64 s[6:7], s[74:75]
	s_cbranch_execz .LBB0_1084
	s_add_i32 s56, s30, -16
	s_lshl_b64 s[30:31], s[56:57], 10
	s_nop 3
	v_cvt_pk_bf16_f32 v22, v22, v23
	v_cvt_pk_bf16_f32 v23, v24, v25
	v_lshl_add_u64 v[24:25], v[26:27], 0, s[30:31]
	global_store_dwordx2 v[24:25], v[22:23], off
.LBB0_1084:
	s_or_b64 exec, exec, s[6:7]
	v_add_u32_e32 v28, v112, v72
	s_nop 3
	ds_read_b128 v[22:25], v28 offset:45056
	v_add_u32_e32 v81, s65, v63
	ds_read_b128 v[82:85], v28 offset:45120
	ds_read_b128 v[86:89], v81 offset:40960
	ds_read_b128 v[90:93], v81 offset:41024
	s_add_i32 s30, s70, s11
	s_cmp_gt_i32 s30, 15
	s_cselect_b64 s[6:7], -1, 0
	s_and_b64 s[74:75], s[0:1], s[6:7]
	s_waitcnt lgkmcnt(1)
	v_mfma_f32_16x16x32_bf16 v[22:25], v[22:25], v[86:89], 0
	s_waitcnt lgkmcnt(0)
	v_mfma_f32_16x16x32_bf16 v[22:25], v[82:85], v[90:93], v[22:25]
	s_and_saveexec_b64 s[6:7], s[74:75]
	s_cbranch_execz .LBB0_1086
	s_add_i32 s56, s30, -16
	s_lshl_b64 s[30:31], s[56:57], 10
	s_nop 3
	v_cvt_pk_bf16_f32 v22, v22, v23
	v_cvt_pk_bf16_f32 v23, v24, v25
	v_lshl_add_u64 v[24:25], v[26:27], 0, s[30:31]
	global_store_dwordx2 v[24:25], v[22:23], off
.LBB0_1086:
	s_or_b64 exec, exec, s[6:7]
	v_add_u32_e32 v28, v112, v71
	s_nop 3
	ds_read_b128 v[22:25], v28 offset:45056
	v_add_u32_e32 v81, s64, v63
	ds_read_b128 v[82:85], v28 offset:45120
	ds_read_b128 v[86:89], v81 offset:40960
	ds_read_b128 v[90:93], v81 offset:41024
	s_add_i32 s11, s71, s11
	s_cmp_gt_i32 s11, 15
	s_cselect_b64 s[6:7], -1, 0
	s_and_b64 s[30:31], s[0:1], s[6:7]
	s_waitcnt lgkmcnt(1)
	v_mfma_f32_16x16x32_bf16 v[22:25], v[22:25], v[86:89], 0
	s_waitcnt lgkmcnt(0)
	v_mfma_f32_16x16x32_bf16 v[22:25], v[82:85], v[90:93], v[22:25]
	s_and_saveexec_b64 s[6:7], s[30:31]
	s_cbranch_execnz .LBB0_1089
	s_or_b64 exec, exec, s[6:7]
	s_cmpk_lg_i32 s72, 0x150
	s_cbranch_scc0 .LBB0_1090

.LBB0_1093:
	v_add_u32_e32 v6, v112, v79
	ds_read_b128 v[2:5], v6 offset:45056
	v_add_u32_e32 v14, s68, v63
	ds_read_b128 v[6:9], v6 offset:45120
	ds_read_b128 v[10:13], v14 offset:40960
	ds_read_b128 v[14:17], v14 offset:41024
	s_mov_b32 s5, 0
	s_waitcnt lgkmcnt(1)
	v_mfma_f32_16x16x32_bf16 v[2:5], v[2:5], v[10:13], 0
	s_waitcnt lgkmcnt(0)
	v_mfma_f32_16x16x32_bf16 v[2:5], v[6:9], v[14:17], v[2:5]
	s_and_saveexec_b64 s[6:7], s[0:1]
	s_cbranch_execz .LBB0_1095
	s_add_i32 s4, s35, 0x1fe0
	s_lshl_b64 s[10:11], s[4:5], 10
	s_nop 3
	v_cvt_pk_bf16_f32 v2, v2, v3
	v_cvt_pk_bf16_f32 v3, v4, v5
	v_lshl_add_u64 v[4:5], v[26:27], 0, s[10:11]
	global_store_dwordx2 v[4:5], v[2:3], off
.LBB0_1095:
	s_or_b64 exec, exec, s[6:7]
	v_add_u32_e32 v6, v112, v74
	s_nop 3
	ds_read_b128 v[2:5], v6 offset:45056
	v_add_u32_e32 v14, s66, v63
	ds_read_b128 v[6:9], v6 offset:45120
	ds_read_b128 v[10:13], v14 offset:40960
	ds_read_b128 v[14:17], v14 offset:41024
	s_waitcnt lgkmcnt(1)
	v_mfma_f32_16x16x32_bf16 v[2:5], v[2:5], v[10:13], 0
	s_waitcnt lgkmcnt(0)
	v_mfma_f32_16x16x32_bf16 v[2:5], v[6:9], v[14:17], v[2:5]
	s_and_saveexec_b64 s[6:7], s[0:1]
	s_cbranch_execz .LBB0_1097
	s_add_i32 s4, s35, 0x1fe1
	s_lshl_b64 s[4:5], s[4:5], 10
	s_nop 3
	v_cvt_pk_bf16_f32 v2, v2, v3
	v_cvt_pk_bf16_f32 v3, v4, v5
	v_lshl_add_u64 v[4:5], v[26:27], 0, s[4:5]
	global_store_dwordx2 v[4:5], v[2:3], off
.LBB0_1097:
	s_or_b64 exec, exec, s[6:7]
	v_add_u32_e32 v6, v112, v72
	s_nop 3
	ds_read_b128 v[2:5], v6 offset:45056
	v_add_u32_e32 v14, s65, v63
	ds_read_b128 v[6:9], v6 offset:45120
	ds_read_b128 v[10:13], v14 offset:40960
	ds_read_b128 v[14:17], v14 offset:41024
	s_mov_b32 s5, 0
	s_waitcnt lgkmcnt(1)
	v_mfma_f32_16x16x32_bf16 v[2:5], v[2:5], v[10:13], 0
	s_waitcnt lgkmcnt(0)
	v_mfma_f32_16x16x32_bf16 v[2:5], v[6:9], v[14:17], v[2:5]
	s_and_saveexec_b64 s[6:7], s[0:1]
	s_cbranch_execz .LBB0_1099
	s_add_i32 s4, s35, 0x1fe2
	s_lshl_b64 s[10:11], s[4:5], 10
	s_nop 3
	v_cvt_pk_bf16_f32 v2, v2, v3
	v_cvt_pk_bf16_f32 v3, v4, v5
	v_lshl_add_u64 v[4:5], v[26:27], 0, s[10:11]
	global_store_dwordx2 v[4:5], v[2:3], off
.LBB0_1099:
	s_or_b64 exec, exec, s[6:7]
	v_add_u32_e32 v6, v112, v71
	s_nop 3
	ds_read_b128 v[2:5], v6 offset:45056
	v_add_u32_e32 v14, s64, v63
	ds_read_b128 v[6:9], v6 offset:45120
	ds_read_b128 v[10:13], v14 offset:40960
	ds_read_b128 v[14:17], v14 offset:41024
	s_waitcnt lgkmcnt(1)
	v_mfma_f32_16x16x32_bf16 v[2:5], v[2:5], v[10:13], 0
	s_waitcnt lgkmcnt(0)
	v_mfma_f32_16x16x32_bf16 v[2:5], v[6:9], v[14:17], v[2:5]
	s_and_saveexec_b64 s[6:7], s[0:1]
	s_cbranch_execz .LBB0_1101
	s_add_i32 s4, s35, 0x1fe3
	s_lshl_b64 s[0:1], s[4:5], 10
	s_nop 3
	v_cvt_pk_bf16_f32 v2, v2, v3
	v_cvt_pk_bf16_f32 v3, v4, v5
	v_lshl_add_u64 v[4:5], v[26:27], 0, s[0:1]
	global_store_dwordx2 v[4:5], v[2:3], off
